# GEMM K-loop heads aligned to 64 bytes (code placement experiment on top of the best version)
# speedup vs baseline: 1.0075x; 1.0075x over previous
; template <class Epi, class Sched, bool ALIGN_EPI = false, bool SP2 = false>
; __device__ __forceinline__ void gemm_phase(LAS unsigned char* lds, const Gemm g, const Sched& S, const Epi& E) {
;     ...
;         const bool has_next = S.next(ui + 1, nxt);
;         const char* nA = has_next ? (const char*)g.A + (size_t)nxt.pm * tstep : cA; const char* nB = has_next ? (const char*)g.Bt + (size_t)nxt.pn * tstep : cB;
;     ...
; #pragma unroll
;         for (int a = 0; a < 2; ++a)
; #pragma unroll
;             for (int b = 0; b < 2; ++b)
; #pragma unroll
;                 for (int m = 0; m < 4; ++m)
; #pragma unroll
;                     for (int n = 0; n < 2; ++n) acc[a][b][m][n] = (f32x4){0.f, 0.f, 0.f, 0.f};
;         cur = nxt; cA = nA; cB = nB; ++ui;
.LBB0_113:
	s_ashr_i32 s17, s16, 31
	s_lshl_b64 s[18:19], s[16:17], 19
	s_add_u32 s18, s68, s18
	s_addc_u32 s19, s69, s19
	s_and_b64 s[20:21], s[0:1], exec
	s_cselect_b32 s17, s19, s25
	s_cselect_b32 s45, s18, s24
	s_ashr_i32 s11, s10, 31
	s_lshl_b64 s[20:21], s[10:11], 19
	s_add_u32 s20, s14, s20
	s_addc_u32 s21, s15, s21
	s_and_b64 s[28:29], s[0:1], exec
	s_cselect_b32 s11, s21, s27
	s_cselect_b32 s46, s20, s26
	s_add_u32 s24, s24, 0x40080
	s_addc_u32 s25, s25, 0
	s_add_u32 s47, s26, 0x100
	v_mov_b32_e32 v0, 0
	s_addc_u32 s48, s27, 0
	s_mov_b32 s49, -2
	v_mov_b32_e32 v1, v0
	v_mov_b32_e32 v2, v0
	v_mov_b32_e32 v3, v0
	v_mov_b32_e32 v4, v0
	v_mov_b32_e32 v5, v0
	v_mov_b32_e32 v6, v0
	v_mov_b32_e32 v7, v0
	v_mov_b32_e32 v8, v0
	v_mov_b32_e32 v9, v0
	v_mov_b32_e32 v10, v0
	v_mov_b32_e32 v11, v0
	v_mov_b32_e32 v16, v0
	v_mov_b32_e32 v17, v0
	v_mov_b32_e32 v18, v0
	v_mov_b32_e32 v19, v0
	v_mov_b32_e32 v24, v0
	v_mov_b32_e32 v25, v0
	v_mov_b32_e32 v26, v0
	v_mov_b32_e32 v27, v0
	v_mov_b32_e32 v32, v0
	v_mov_b32_e32 v33, v0
	v_mov_b32_e32 v34, v0
	v_mov_b32_e32 v35, v0
	v_mov_b32_e32 v40, v0
	v_mov_b32_e32 v41, v0
	v_mov_b32_e32 v42, v0
	v_mov_b32_e32 v43, v0
	v_mov_b32_e32 v48, v0
	v_mov_b32_e32 v49, v0
	v_mov_b32_e32 v50, v0
	v_mov_b32_e32 v51, v0
	v_mov_b32_e32 v12, v0
	v_mov_b32_e32 v13, v0
	v_mov_b32_e32 v14, v0
	v_mov_b32_e32 v15, v0
	v_mov_b32_e32 v20, v0
	v_mov_b32_e32 v21, v0
	v_mov_b32_e32 v22, v0
	v_mov_b32_e32 v23, v0
	v_mov_b32_e32 v28, v0
	v_mov_b32_e32 v29, v0
	v_mov_b32_e32 v30, v0
	v_mov_b32_e32 v31, v0
	v_mov_b32_e32 v36, v0
	v_mov_b32_e32 v37, v0
	v_mov_b32_e32 v38, v0
	v_mov_b32_e32 v39, v0
	v_mov_b32_e32 v44, v0
	v_mov_b32_e32 v45, v0
	v_mov_b32_e32 v46, v0
	v_mov_b32_e32 v47, v0
	v_mov_b32_e32 v52, v0
	v_mov_b32_e32 v53, v0
	v_mov_b32_e32 v54, v0
	v_mov_b32_e32 v55, v0
	v_mov_b32_e32 v56, v0
	v_mov_b32_e32 v57, v0
	v_mov_b32_e32 v58, v0
	v_mov_b32_e32 v59, v0
	v_mov_b32_e32 v60, v0
	v_mov_b32_e32 v61, v0
	v_mov_b32_e32 v62, v0
	v_mov_b32_e32 v63, v0
	v_mov_b32_e32 v64, v0
	v_mov_b32_e32 v65, v0
	v_mov_b32_e32 v66, v0
	v_mov_b32_e32 v67, v0
	v_mov_b32_e32 v68, v0
	v_mov_b32_e32 v69, v0
	v_mov_b32_e32 v70, v0
	v_mov_b32_e32 v71, v0
	v_mov_b32_e32 v72, v0
	v_mov_b32_e32 v73, v0
	v_mov_b32_e32 v74, v0
	v_mov_b32_e32 v75, v0
	v_mov_b32_e32 v80, v0
	v_mov_b32_e32 v81, v0
	v_mov_b32_e32 v82, v0
	v_mov_b32_e32 v83, v0
	v_mov_b32_e32 v88, v0
	v_mov_b32_e32 v89, v0
	v_mov_b32_e32 v90, v0
	v_mov_b32_e32 v91, v0
	v_mov_b32_e32 v96, v0
	v_mov_b32_e32 v97, v0
	v_mov_b32_e32 v98, v0
	v_mov_b32_e32 v99, v0
	v_mov_b32_e32 v104, v0
	v_mov_b32_e32 v105, v0
	v_mov_b32_e32 v106, v0
	v_mov_b32_e32 v107, v0
	v_mov_b32_e32 v112, v0
	v_mov_b32_e32 v113, v0
	v_mov_b32_e32 v114, v0
	v_mov_b32_e32 v115, v0
	v_mov_b32_e32 v76, v0
	v_mov_b32_e32 v77, v0
	v_mov_b32_e32 v78, v0
	v_mov_b32_e32 v79, v0
	v_mov_b32_e32 v84, v0
	v_mov_b32_e32 v85, v0
	v_mov_b32_e32 v86, v0
	v_mov_b32_e32 v87, v0
	v_mov_b32_e32 v92, v0
	v_mov_b32_e32 v93, v0
	v_mov_b32_e32 v94, v0
	v_mov_b32_e32 v95, v0
	v_mov_b32_e32 v100, v0
	v_mov_b32_e32 v101, v0
	v_mov_b32_e32 v102, v0
	v_mov_b32_e32 v103, v0
	v_mov_b32_e32 v108, v0
	v_mov_b32_e32 v109, v0
	v_mov_b32_e32 v110, v0
	v_mov_b32_e32 v111, v0
	v_mov_b32_e32 v116, v0
	v_mov_b32_e32 v117, v0
	v_mov_b32_e32 v118, v0
	v_mov_b32_e32 v119, v0
	v_mov_b32_e32 v120, v0
	v_mov_b32_e32 v121, v0
	v_mov_b32_e32 v122, v0
	v_mov_b32_e32 v123, v0
	v_mov_b32_e32 v124, v0
	v_mov_b32_e32 v125, v0
	v_mov_b32_e32 v126, v0
	v_mov_b32_e32 v127, v0
	.p2align 6

; template <class Epi, class Sched, bool ALIGN_EPI = false, bool SP2 = false>
; __device__ __forceinline__ void gemm_phase(LAS unsigned char* lds, const Gemm g, const Sched& S, const Epi& E) {
;     ...
;         const bool has_next = S.next(ui + 1, nxt);
;         const char* nA = has_next ? (const char*)g.A + (size_t)nxt.pm * tstep : cA; const char* nB = has_next ? (const char*)g.Bt + (size_t)nxt.pn * tstep : cB;
;     ...
; #pragma unroll
;         for (int a = 0; a < 2; ++a)
; #pragma unroll
;             for (int b = 0; b < 2; ++b)
; #pragma unroll
;                 for (int m = 0; m < 4; ++m)
; #pragma unroll
;                     for (int n = 0; n < 2; ++n) acc[a][b][m][n] = (f32x4){0.f, 0.f, 0.f, 0.f};
;         cur = nxt; cA = nA; cB = nB; ++ui;
.LBB0_129:
	s_ashr_i32 s15, s14, 31
	s_lshl_b64 s[16:17], s[14:15], 17
	s_add_u32 s16, s43, s16
	s_addc_u32 s17, s44, s17
	s_and_b64 s[18:19], s[0:1], exec
	s_cselect_b32 s15, s17, s25
	s_cselect_b32 s58, s16, s24
	s_ashr_i32 s11, s10, 31
	s_lshl_b64 s[18:19], s[10:11], 17
	s_add_u32 s18, s12, s18
	s_addc_u32 s19, s13, s19
	s_and_b64 s[26:27], s[0:1], exec
	v_mov_b32_e32 v0, 0
	s_cselect_b32 s11, s19, s23
	s_cselect_b32 s59, s18, s22
	s_mov_b32 s30, 0
	s_mov_b64 s[26:27], -1
	s_mov_b64 s[28:29], 0
	v_mov_b32_e32 v1, v0
	v_mov_b32_e32 v2, v0
	v_mov_b32_e32 v3, v0
	v_mov_b32_e32 v4, v0
	v_mov_b32_e32 v5, v0
	v_mov_b32_e32 v6, v0
	v_mov_b32_e32 v7, v0
	v_mov_b32_e32 v8, v0
	v_mov_b32_e32 v9, v0
	v_mov_b32_e32 v10, v0
	v_mov_b32_e32 v11, v0
	v_mov_b32_e32 v16, v0
	v_mov_b32_e32 v17, v0
	v_mov_b32_e32 v18, v0
	v_mov_b32_e32 v19, v0
	v_mov_b32_e32 v24, v0
	v_mov_b32_e32 v25, v0
	v_mov_b32_e32 v26, v0
	v_mov_b32_e32 v27, v0
	v_mov_b32_e32 v32, v0
	v_mov_b32_e32 v33, v0
	v_mov_b32_e32 v34, v0
	v_mov_b32_e32 v35, v0
	v_mov_b32_e32 v40, v0
	v_mov_b32_e32 v41, v0
	v_mov_b32_e32 v42, v0
	v_mov_b32_e32 v43, v0
	v_mov_b32_e32 v48, v0
	v_mov_b32_e32 v49, v0
	v_mov_b32_e32 v50, v0
	v_mov_b32_e32 v51, v0
	v_mov_b32_e32 v12, v0
	v_mov_b32_e32 v13, v0
	v_mov_b32_e32 v14, v0
	v_mov_b32_e32 v15, v0
	v_mov_b32_e32 v20, v0
	v_mov_b32_e32 v21, v0
	v_mov_b32_e32 v22, v0
	v_mov_b32_e32 v23, v0
	v_mov_b32_e32 v28, v0
	v_mov_b32_e32 v29, v0
	v_mov_b32_e32 v30, v0
	v_mov_b32_e32 v31, v0
	v_mov_b32_e32 v36, v0
	v_mov_b32_e32 v37, v0
	v_mov_b32_e32 v38, v0
	v_mov_b32_e32 v39, v0
	v_mov_b32_e32 v44, v0
	v_mov_b32_e32 v45, v0
	v_mov_b32_e32 v46, v0
	v_mov_b32_e32 v47, v0
	v_mov_b32_e32 v52, v0
	v_mov_b32_e32 v53, v0
	v_mov_b32_e32 v54, v0
	v_mov_b32_e32 v55, v0
	v_mov_b32_e32 v56, v0
	v_mov_b32_e32 v57, v0
	v_mov_b32_e32 v58, v0
	v_mov_b32_e32 v59, v0
	v_mov_b32_e32 v60, v0
	v_mov_b32_e32 v61, v0
	v_mov_b32_e32 v62, v0
	v_mov_b32_e32 v63, v0
	v_mov_b32_e32 v64, v0
	v_mov_b32_e32 v65, v0
	v_mov_b32_e32 v66, v0
	v_mov_b32_e32 v67, v0
	v_mov_b32_e32 v68, v0
	v_mov_b32_e32 v69, v0
	v_mov_b32_e32 v70, v0
	v_mov_b32_e32 v71, v0
	v_mov_b32_e32 v72, v0
	v_mov_b32_e32 v73, v0
	v_mov_b32_e32 v74, v0
	v_mov_b32_e32 v75, v0
	v_mov_b32_e32 v80, v0
	v_mov_b32_e32 v81, v0
	v_mov_b32_e32 v82, v0
	v_mov_b32_e32 v83, v0
	v_mov_b32_e32 v88, v0
	v_mov_b32_e32 v89, v0
	v_mov_b32_e32 v90, v0
	v_mov_b32_e32 v91, v0
	v_mov_b32_e32 v96, v0
	v_mov_b32_e32 v97, v0
	v_mov_b32_e32 v98, v0
	v_mov_b32_e32 v99, v0
	v_mov_b32_e32 v104, v0
	v_mov_b32_e32 v105, v0
	v_mov_b32_e32 v106, v0
	v_mov_b32_e32 v107, v0
	v_mov_b32_e32 v112, v0
	v_mov_b32_e32 v113, v0
	v_mov_b32_e32 v114, v0
	v_mov_b32_e32 v115, v0
	v_mov_b32_e32 v76, v0
	v_mov_b32_e32 v77, v0
	v_mov_b32_e32 v78, v0
	v_mov_b32_e32 v79, v0
	v_mov_b32_e32 v84, v0
	v_mov_b32_e32 v85, v0
	v_mov_b32_e32 v86, v0
	v_mov_b32_e32 v87, v0
	v_mov_b32_e32 v92, v0
	v_mov_b32_e32 v93, v0
	v_mov_b32_e32 v94, v0
	v_mov_b32_e32 v95, v0
	v_mov_b32_e32 v100, v0
	v_mov_b32_e32 v101, v0
	v_mov_b32_e32 v102, v0
	v_mov_b32_e32 v103, v0
	v_mov_b32_e32 v108, v0
	v_mov_b32_e32 v109, v0
	v_mov_b32_e32 v110, v0
	v_mov_b32_e32 v111, v0
	v_mov_b32_e32 v116, v0
	v_mov_b32_e32 v117, v0
	v_mov_b32_e32 v118, v0
	v_mov_b32_e32 v119, v0
	v_mov_b32_e32 v120, v0
	v_mov_b32_e32 v121, v0
	v_mov_b32_e32 v122, v0
	v_mov_b32_e32 v123, v0
	v_mov_b32_e32 v124, v0
	v_mov_b32_e32 v125, v0
	v_mov_b32_e32 v126, v0
	v_mov_b32_e32 v127, v0
	.p2align 6

; template <class Epi, class Sched, bool ALIGN_EPI = false, bool SP2 = false>
; __device__ __forceinline__ void gemm_phase(LAS unsigned char* lds, const Gemm g, const Sched& S, const Epi& E) {
;     ...
;         const bool has_next = S.next(ui + 1, nxt);
;         const char* nA = has_next ? (const char*)g.A + (size_t)nxt.pm * tstep : cA; const char* nB = has_next ? (const char*)g.Bt + (size_t)nxt.pn * tstep : cB;
;         for (int t = 0; t < nt; t += 2) {
;             const bool last = (t == nt - 2);
;             const char* a1 = cA + (size_t)(t + 1) * kstep;
;             const char* a2 = last ? nA : cA + (size_t)(t + 2) * kstep; const char* b2 = last ? nB : cB + (size_t)(t + 2) * kstep;
;             const char* a3 = a2 + kstep; const char* b3 = b2 + kstep;
;             if (last && has_next) S.a_ready(nxt);
;     ...
; #pragma unroll
;         for (int a = 0; a < 2; ++a)
; #pragma unroll
;             for (int b = 0; b < 2; ++b)
; #pragma unroll
;                 for (int m = 0; m < 4; ++m)
; #pragma unroll
;                     for (int n = 0; n < 2; ++n) acc[a][b][m][n] = (f32x4){0.f, 0.f, 0.f, 0.f};
;         cur = nxt; cA = nA; cB = nB; ++ui;
.LBB0_512:
	s_ashr_i32 s21, s20, 31
	s_lshl_b64 s[22:23], s[20:21], 19
	s_add_u32 s22, s68, s22
	s_addc_u32 s23, s69, s23
	s_and_b64 s[24:25], s[6:7], exec
	s_cselect_b32 s21, s23, s31
	s_cselect_b32 s27, s22, s30
	s_ashr_i32 s19, s18, 31
	s_lshl_b64 s[24:25], s[18:19], 19
	v_readlane_b32 s36, v249, 1
	v_readlane_b32 s37, v249, 2
	s_add_u32 s24, s36, s24
	s_addc_u32 s25, s37, s25
	s_and_b64 s[36:37], s[6:7], exec
	s_cselect_b32 s19, s25, s35
	s_cselect_b32 s29, s24, s34
	s_add_u32 s30, s30, 0x40080
	s_addc_u32 s31, s31, 0
	s_add_u32 s55, s34, 0x100
	v_mov_b32_e32 v0, 0
	s_addc_u32 s56, s35, 0
	s_mov_b32 s57, -2
	s_waitcnt lgkmcnt(0)
	v_mov_b32_e32 v1, v0
	v_mov_b32_e32 v2, v0
	v_mov_b32_e32 v3, v0
	v_mov_b32_e32 v4, v0
	v_mov_b32_e32 v5, v0
	v_mov_b32_e32 v6, v0
	v_mov_b32_e32 v7, v0
	v_mov_b32_e32 v16, v0
	v_mov_b32_e32 v17, v0
	v_mov_b32_e32 v18, v0
	v_mov_b32_e32 v19, v0
	v_mov_b32_e32 v20, v0
	v_mov_b32_e32 v21, v0
	v_mov_b32_e32 v22, v0
	v_mov_b32_e32 v23, v0
	v_mov_b32_e32 v32, v0
	v_mov_b32_e32 v33, v0
	v_mov_b32_e32 v34, v0
	v_mov_b32_e32 v35, v0
	v_mov_b32_e32 v36, v0
	v_mov_b32_e32 v37, v0
	v_mov_b32_e32 v38, v0
	v_mov_b32_e32 v39, v0
	v_mov_b32_e32 v48, v0
	v_mov_b32_e32 v49, v0
	v_mov_b32_e32 v50, v0
	v_mov_b32_e32 v51, v0
	v_mov_b32_e32 v52, v0
	v_mov_b32_e32 v53, v0
	v_mov_b32_e32 v54, v0
	v_mov_b32_e32 v55, v0
	v_mov_b32_e32 v8, v0
	v_mov_b32_e32 v9, v0
	v_mov_b32_e32 v10, v0
	v_mov_b32_e32 v11, v0
	v_mov_b32_e32 v12, v0
	v_mov_b32_e32 v13, v0
	v_mov_b32_e32 v14, v0
	v_mov_b32_e32 v15, v0
	v_mov_b32_e32 v24, v0
	v_mov_b32_e32 v25, v0
	v_mov_b32_e32 v26, v0
	v_mov_b32_e32 v27, v0
	v_mov_b32_e32 v28, v0
	v_mov_b32_e32 v29, v0
	v_mov_b32_e32 v30, v0
	v_mov_b32_e32 v31, v0
	v_mov_b32_e32 v40, v0
	v_mov_b32_e32 v41, v0
	v_mov_b32_e32 v42, v0
	v_mov_b32_e32 v43, v0
	v_mov_b32_e32 v44, v0
	v_mov_b32_e32 v45, v0
	v_mov_b32_e32 v46, v0
	v_mov_b32_e32 v47, v0
	v_mov_b32_e32 v56, v0
	v_mov_b32_e32 v57, v0
	v_mov_b32_e32 v58, v0
	v_mov_b32_e32 v59, v0
	v_mov_b32_e32 v60, v0
	v_mov_b32_e32 v61, v0
	v_mov_b32_e32 v62, v0
	v_mov_b32_e32 v63, v0
	v_mov_b32_e32 v64, v0
	v_mov_b32_e32 v65, v0
	v_mov_b32_e32 v66, v0
	v_mov_b32_e32 v67, v0
	v_mov_b32_e32 v68, v0
	v_mov_b32_e32 v69, v0
	v_mov_b32_e32 v70, v0
	v_mov_b32_e32 v71, v0
	v_mov_b32_e32 v80, v0
	v_mov_b32_e32 v81, v0
	v_mov_b32_e32 v82, v0
	v_mov_b32_e32 v83, v0
	v_mov_b32_e32 v84, v0
	v_mov_b32_e32 v85, v0
	v_mov_b32_e32 v86, v0
	v_mov_b32_e32 v87, v0
	v_mov_b32_e32 v96, v0
	v_mov_b32_e32 v97, v0
	v_mov_b32_e32 v98, v0
	v_mov_b32_e32 v99, v0
	v_mov_b32_e32 v100, v0
	v_mov_b32_e32 v101, v0
	v_mov_b32_e32 v102, v0
	v_mov_b32_e32 v103, v0
	v_mov_b32_e32 v112, v0
	v_mov_b32_e32 v113, v0
	v_mov_b32_e32 v114, v0
	v_mov_b32_e32 v115, v0
	v_mov_b32_e32 v116, v0
	v_mov_b32_e32 v117, v0
	v_mov_b32_e32 v118, v0
	v_mov_b32_e32 v119, v0
	v_mov_b32_e32 v72, v0
	v_mov_b32_e32 v73, v0
	v_mov_b32_e32 v74, v0
	v_mov_b32_e32 v75, v0
	v_mov_b32_e32 v76, v0
	v_mov_b32_e32 v77, v0
	v_mov_b32_e32 v78, v0
	v_mov_b32_e32 v79, v0
	v_mov_b32_e32 v88, v0
	v_mov_b32_e32 v89, v0
	v_mov_b32_e32 v90, v0
	v_mov_b32_e32 v91, v0
	v_mov_b32_e32 v92, v0
	v_mov_b32_e32 v93, v0
	v_mov_b32_e32 v94, v0
	v_mov_b32_e32 v95, v0
	v_mov_b32_e32 v104, v0
	v_mov_b32_e32 v105, v0
	v_mov_b32_e32 v106, v0
	v_mov_b32_e32 v107, v0
	v_mov_b32_e32 v108, v0
	v_mov_b32_e32 v109, v0
	v_mov_b32_e32 v110, v0
	v_mov_b32_e32 v111, v0
	v_mov_b32_e32 v120, v0
	v_mov_b32_e32 v121, v0
	v_mov_b32_e32 v122, v0
	v_mov_b32_e32 v123, v0
	v_mov_b32_e32 v124, v0
	v_mov_b32_e32 v125, v0
	v_mov_b32_e32 v126, v0
	v_mov_b32_e32 v127, v0
	.p2align 6

; template <class Epi, class Sched, bool ALIGN_EPI = false, bool SP2 = false>
; __device__ __forceinline__ void gemm_phase(LAS unsigned char* lds, const Gemm g, const Sched& S, const Epi& E) {
;     ...
;         const bool has_next = S.next(ui + 1, nxt);
;         const char* nA = has_next ? (const char*)g.A + (size_t)nxt.pm * tstep : cA; const char* nB = has_next ? (const char*)g.Bt + (size_t)nxt.pn * tstep : cB;
;         for (int t = 0; t < nt; t += 2) {
;             const bool last = (t == nt - 2);
;             const char* a1 = cA + (size_t)(t + 1) * kstep;
;             const char* a2 = last ? nA : cA + (size_t)(t + 2) * kstep; const char* b2 = last ? nB : cB + (size_t)(t + 2) * kstep;
;             const char* a3 = a2 + kstep; const char* b3 = b2 + kstep;
;             if (last && has_next) S.a_ready(nxt);
;     ...
; #pragma unroll
;         for (int a = 0; a < 2; ++a)
; #pragma unroll
;             for (int b = 0; b < 2; ++b)
; #pragma unroll
;                 for (int m = 0; m < 4; ++m)
; #pragma unroll
;                     for (int n = 0; n < 2; ++n) acc[a][b][m][n] = (f32x4){0.f, 0.f, 0.f, 0.f};
;         cur = nxt; cA = nA; cB = nB; ++ui;
.LBB0_606:
	s_ashr_i32 s23, s22, 31
	s_lshl_b64 s[24:25], s[22:23], 19
	s_add_u32 s24, s94, s24
	s_addc_u32 s25, s95, s25
	s_and_b64 s[26:27], s[4:5], exec
	s_cselect_b32 s23, s25, s35
	s_cselect_b32 s29, s24, s34
	s_ashr_i32 s21, s20, 31
	s_lshl_b64 s[26:27], s[20:21], 19
	s_add_u32 s26, s70, s26
	s_addc_u32 s27, s71, s27
	s_and_b64 s[38:39], s[4:5], exec
	s_cselect_b32 s21, s27, s37
	s_cselect_b32 s52, s26, s36
	s_add_u32 s34, s34, 0x40080
	s_addc_u32 s35, s35, 0
	s_add_u32 s53, s36, 0x100
	v_mov_b32_e32 v0, 0
	s_addc_u32 s54, s37, 0
	s_mov_b32 s55, -2
	s_waitcnt lgkmcnt(0)
	v_mov_b32_e32 v1, v0
	v_mov_b32_e32 v2, v0
	v_mov_b32_e32 v3, v0
	v_mov_b32_e32 v4, v0
	v_mov_b32_e32 v5, v0
	v_mov_b32_e32 v6, v0
	v_mov_b32_e32 v7, v0
	v_mov_b32_e32 v16, v0
	v_mov_b32_e32 v17, v0
	v_mov_b32_e32 v18, v0
	v_mov_b32_e32 v19, v0
	v_mov_b32_e32 v20, v0
	v_mov_b32_e32 v21, v0
	v_mov_b32_e32 v22, v0
	v_mov_b32_e32 v23, v0
	v_mov_b32_e32 v32, v0
	v_mov_b32_e32 v33, v0
	v_mov_b32_e32 v34, v0
	v_mov_b32_e32 v35, v0
	v_mov_b32_e32 v36, v0
	v_mov_b32_e32 v37, v0
	v_mov_b32_e32 v38, v0
	v_mov_b32_e32 v39, v0
	v_mov_b32_e32 v48, v0
	v_mov_b32_e32 v49, v0
	v_mov_b32_e32 v50, v0
	v_mov_b32_e32 v51, v0
	v_mov_b32_e32 v52, v0
	v_mov_b32_e32 v53, v0
	v_mov_b32_e32 v54, v0
	v_mov_b32_e32 v55, v0
	v_mov_b32_e32 v8, v0
	v_mov_b32_e32 v9, v0
	v_mov_b32_e32 v10, v0
	v_mov_b32_e32 v11, v0
	v_mov_b32_e32 v12, v0
	v_mov_b32_e32 v13, v0
	v_mov_b32_e32 v14, v0
	v_mov_b32_e32 v15, v0
	v_mov_b32_e32 v24, v0
	v_mov_b32_e32 v25, v0
	v_mov_b32_e32 v26, v0
	v_mov_b32_e32 v27, v0
	v_mov_b32_e32 v28, v0
	v_mov_b32_e32 v29, v0
	v_mov_b32_e32 v30, v0
	v_mov_b32_e32 v31, v0
	v_mov_b32_e32 v40, v0
	v_mov_b32_e32 v41, v0
	v_mov_b32_e32 v42, v0
	v_mov_b32_e32 v43, v0
	v_mov_b32_e32 v44, v0
	v_mov_b32_e32 v45, v0
	v_mov_b32_e32 v46, v0
	v_mov_b32_e32 v47, v0
	v_mov_b32_e32 v56, v0
	v_mov_b32_e32 v57, v0
	v_mov_b32_e32 v58, v0
	v_mov_b32_e32 v59, v0
	v_mov_b32_e32 v60, v0
	v_mov_b32_e32 v61, v0
	v_mov_b32_e32 v62, v0
	v_mov_b32_e32 v63, v0
	v_mov_b32_e32 v64, v0
	v_mov_b32_e32 v65, v0
	v_mov_b32_e32 v66, v0
	v_mov_b32_e32 v67, v0
	v_mov_b32_e32 v68, v0
	v_mov_b32_e32 v69, v0
	v_mov_b32_e32 v70, v0
	v_mov_b32_e32 v71, v0
	v_mov_b32_e32 v80, v0
	v_mov_b32_e32 v81, v0
	v_mov_b32_e32 v82, v0
	v_mov_b32_e32 v83, v0
	v_mov_b32_e32 v84, v0
	v_mov_b32_e32 v85, v0
	v_mov_b32_e32 v86, v0
	v_mov_b32_e32 v87, v0
	v_mov_b32_e32 v96, v0
	v_mov_b32_e32 v97, v0
	v_mov_b32_e32 v98, v0
	v_mov_b32_e32 v99, v0
	v_mov_b32_e32 v100, v0
	v_mov_b32_e32 v101, v0
	v_mov_b32_e32 v102, v0
	v_mov_b32_e32 v103, v0
	v_mov_b32_e32 v112, v0
	v_mov_b32_e32 v113, v0
	v_mov_b32_e32 v114, v0
	v_mov_b32_e32 v115, v0
	v_mov_b32_e32 v116, v0
	v_mov_b32_e32 v117, v0
	v_mov_b32_e32 v118, v0
	v_mov_b32_e32 v119, v0
	v_mov_b32_e32 v72, v0
	v_mov_b32_e32 v73, v0
	v_mov_b32_e32 v74, v0
	v_mov_b32_e32 v75, v0
	v_mov_b32_e32 v76, v0
	v_mov_b32_e32 v77, v0
	v_mov_b32_e32 v78, v0
	v_mov_b32_e32 v79, v0
	v_mov_b32_e32 v88, v0
	v_mov_b32_e32 v89, v0
	v_mov_b32_e32 v90, v0
	v_mov_b32_e32 v91, v0
	v_mov_b32_e32 v92, v0
	v_mov_b32_e32 v93, v0
	v_mov_b32_e32 v94, v0
	v_mov_b32_e32 v95, v0
	v_mov_b32_e32 v104, v0
	v_mov_b32_e32 v105, v0
	v_mov_b32_e32 v106, v0
	v_mov_b32_e32 v107, v0
	v_mov_b32_e32 v108, v0
	v_mov_b32_e32 v109, v0
	v_mov_b32_e32 v110, v0
	v_mov_b32_e32 v111, v0
	v_mov_b32_e32 v120, v0
	v_mov_b32_e32 v121, v0
	v_mov_b32_e32 v122, v0
	v_mov_b32_e32 v123, v0
	v_mov_b32_e32 v124, v0
	v_mov_b32_e32 v125, v0
	v_mov_b32_e32 v126, v0
	v_mov_b32_e32 v127, v0
	.p2align 6
